# same stack without the peeled first K-iteration (keeps accumulator zeroing)
# speedup vs baseline: 1.0028x; 1.0028x over previous
.LBB0_839:
	s_lshl_b32 s59, s57, 18
	s_and_b64 s[6:7], s[6:7], exec
	v_mov_b32_e32 v2, 0
	s_cselect_b32 s6, s59, s79
	s_add_i32 s7, s79, 0x30800
	s_addk_i32 s78, 0x100
	s_mov_b32 s79, -2
	v_mov_b32_e32 v3, v2
	v_mov_b32_e32 v4, v2
	v_mov_b32_e32 v5, v2
	v_mov_b32_e32 v6, v2
	v_mov_b32_e32 v7, v2
	v_mov_b32_e32 v8, v2
	v_mov_b32_e32 v9, v2
	v_mov_b32_e32 v14, v2
	v_mov_b32_e32 v15, v2
	v_mov_b32_e32 v16, v2
	v_mov_b32_e32 v17, v2
	v_mov_b32_e32 v22, v2
	v_mov_b32_e32 v23, v2
	v_mov_b32_e32 v24, v2
	v_mov_b32_e32 v25, v2
	v_mov_b32_e32 v30, v2
	v_mov_b32_e32 v31, v2
	v_mov_b32_e32 v32, v2
	v_mov_b32_e32 v33, v2
	v_mov_b32_e32 v38, v2
	v_mov_b32_e32 v39, v2
	v_mov_b32_e32 v40, v2
	v_mov_b32_e32 v41, v2
	v_mov_b32_e32 v46, v2
	v_mov_b32_e32 v47, v2
	v_mov_b32_e32 v48, v2
	v_mov_b32_e32 v49, v2
	v_mov_b32_e32 v54, v2
	v_mov_b32_e32 v55, v2
	v_mov_b32_e32 v56, v2
	v_mov_b32_e32 v57, v2
	v_mov_b32_e32 v10, v2
	v_mov_b32_e32 v11, v2
	v_mov_b32_e32 v12, v2
	v_mov_b32_e32 v13, v2
	v_mov_b32_e32 v230, v2
	v_mov_b32_e32 v231, v2
	v_mov_b32_e32 v232, v2
	v_mov_b32_e32 v233, v2
	v_mov_b32_e32 v26, v2
	v_mov_b32_e32 v27, v2
	v_mov_b32_e32 v28, v2
	v_mov_b32_e32 v29, v2
	v_mov_b32_e32 v34, v2
	v_mov_b32_e32 v35, v2
	v_mov_b32_e32 v36, v2
	v_mov_b32_e32 v37, v2
	v_mov_b32_e32 v42, v2
	v_mov_b32_e32 v43, v2
	v_mov_b32_e32 v44, v2
	v_mov_b32_e32 v45, v2
	v_mov_b32_e32 v50, v2
	v_mov_b32_e32 v51, v2
	v_mov_b32_e32 v52, v2
	v_mov_b32_e32 v53, v2
	v_mov_b32_e32 v58, v2
	v_mov_b32_e32 v59, v2
	v_mov_b32_e32 v60, v2
	v_mov_b32_e32 v61, v2
	v_mov_b32_e32 v62, v2
	v_mov_b32_e32 v63, v2
	v_mov_b32_e32 v64, v2
	v_mov_b32_e32 v65, v2
	v_mov_b32_e32 v18, v2
	v_mov_b32_e32 v19, v2
	v_mov_b32_e32 v20, v2
	v_mov_b32_e32 v21, v2
	v_mov_b32_e32 v70, v2
	v_mov_b32_e32 v71, v2
	v_mov_b32_e32 v72, v2
	v_mov_b32_e32 v73, v2
	v_mov_b32_e32 v78, v2
	v_mov_b32_e32 v79, v2
	v_mov_b32_e32 v80, v2
	v_mov_b32_e32 v81, v2
	v_mov_b32_e32 v86, v2
	v_mov_b32_e32 v87, v2
	v_mov_b32_e32 v88, v2
	v_mov_b32_e32 v89, v2
	v_mov_b32_e32 v94, v2
	v_mov_b32_e32 v95, v2
	v_mov_b32_e32 v96, v2
	v_mov_b32_e32 v97, v2
	v_mov_b32_e32 v102, v2
	v_mov_b32_e32 v103, v2
	v_mov_b32_e32 v104, v2
	v_mov_b32_e32 v105, v2
	v_mov_b32_e32 v110, v2
	v_mov_b32_e32 v111, v2
	v_mov_b32_e32 v112, v2
	v_mov_b32_e32 v113, v2
	v_mov_b32_e32 v118, v2
	v_mov_b32_e32 v119, v2
	v_mov_b32_e32 v120, v2
	v_mov_b32_e32 v121, v2
	v_mov_b32_e32 v74, v2
	v_mov_b32_e32 v75, v2
	v_mov_b32_e32 v76, v2
	v_mov_b32_e32 v77, v2
	v_mov_b32_e32 v82, v2
	v_mov_b32_e32 v83, v2
	v_mov_b32_e32 v84, v2
	v_mov_b32_e32 v85, v2
	v_mov_b32_e32 v90, v2
	v_mov_b32_e32 v91, v2
	v_mov_b32_e32 v92, v2
	v_mov_b32_e32 v93, v2
	v_mov_b32_e32 v98, v2
	v_mov_b32_e32 v99, v2
	v_mov_b32_e32 v100, v2
	v_mov_b32_e32 v101, v2
	v_mov_b32_e32 v106, v2
	v_mov_b32_e32 v107, v2
	v_mov_b32_e32 v108, v2
	v_mov_b32_e32 v109, v2
	v_mov_b32_e32 v114, v2
	v_mov_b32_e32 v115, v2
	v_mov_b32_e32 v116, v2
	v_mov_b32_e32 v117, v2
	v_mov_b32_e32 v122, v2
	v_mov_b32_e32 v123, v2
	v_mov_b32_e32 v124, v2
	v_mov_b32_e32 v125, v2
	v_mov_b32_e32 v126, v2
	v_mov_b32_e32 v127, v2
	v_mov_b32_e32 v128, v2
	v_mov_b32_e32 v129, v2

.LBB0_1723:
	s_lshl_b32 s73, s59, 18
	s_and_b64 s[6:7], s[6:7], exec
	v_mov_b32_e32 v2, 0
	s_cselect_b32 s6, s73, s85
	s_add_i32 s7, s85, 0x30800
	s_addk_i32 s84, 0x100
	s_mov_b32 s85, -2
	v_mov_b32_e32 v3, v2
	v_mov_b32_e32 v4, v2
	v_mov_b32_e32 v5, v2
	v_mov_b32_e32 v6, v2
	v_mov_b32_e32 v7, v2
	v_mov_b32_e32 v8, v2
	v_mov_b32_e32 v9, v2
	v_mov_b32_e32 v14, v2
	v_mov_b32_e32 v15, v2
	v_mov_b32_e32 v16, v2
	v_mov_b32_e32 v17, v2
	v_mov_b32_e32 v22, v2
	v_mov_b32_e32 v23, v2
	v_mov_b32_e32 v24, v2
	v_mov_b32_e32 v25, v2
	v_mov_b32_e32 v30, v2
	v_mov_b32_e32 v31, v2
	v_mov_b32_e32 v32, v2
	v_mov_b32_e32 v33, v2
	v_mov_b32_e32 v38, v2
	v_mov_b32_e32 v39, v2
	v_mov_b32_e32 v40, v2
	v_mov_b32_e32 v41, v2
	v_mov_b32_e32 v46, v2
	v_mov_b32_e32 v47, v2
	v_mov_b32_e32 v48, v2
	v_mov_b32_e32 v49, v2
	v_mov_b32_e32 v54, v2
	v_mov_b32_e32 v55, v2
	v_mov_b32_e32 v56, v2
	v_mov_b32_e32 v57, v2
	v_mov_b32_e32 v10, v2
	v_mov_b32_e32 v11, v2
	v_mov_b32_e32 v12, v2
	v_mov_b32_e32 v13, v2
	v_mov_b32_e32 v230, v2
	v_mov_b32_e32 v231, v2
	v_mov_b32_e32 v232, v2
	v_mov_b32_e32 v233, v2
	v_mov_b32_e32 v26, v2
	v_mov_b32_e32 v27, v2
	v_mov_b32_e32 v28, v2
	v_mov_b32_e32 v29, v2
	v_mov_b32_e32 v34, v2
	v_mov_b32_e32 v35, v2
	v_mov_b32_e32 v36, v2
	v_mov_b32_e32 v37, v2
	v_mov_b32_e32 v42, v2
	v_mov_b32_e32 v43, v2
	v_mov_b32_e32 v44, v2
	v_mov_b32_e32 v45, v2
	v_mov_b32_e32 v50, v2
	v_mov_b32_e32 v51, v2
	v_mov_b32_e32 v52, v2
	v_mov_b32_e32 v53, v2
	v_mov_b32_e32 v58, v2
	v_mov_b32_e32 v59, v2
	v_mov_b32_e32 v60, v2
	v_mov_b32_e32 v61, v2
	v_mov_b32_e32 v62, v2
	v_mov_b32_e32 v63, v2
	v_mov_b32_e32 v64, v2
	v_mov_b32_e32 v65, v2
	v_mov_b32_e32 v18, v2
	v_mov_b32_e32 v19, v2
	v_mov_b32_e32 v20, v2
	v_mov_b32_e32 v21, v2
	v_mov_b32_e32 v70, v2
	v_mov_b32_e32 v71, v2
	v_mov_b32_e32 v72, v2
	v_mov_b32_e32 v73, v2
	v_mov_b32_e32 v78, v2
	v_mov_b32_e32 v79, v2
	v_mov_b32_e32 v80, v2
	v_mov_b32_e32 v81, v2
	v_mov_b32_e32 v86, v2
	v_mov_b32_e32 v87, v2
	v_mov_b32_e32 v88, v2
	v_mov_b32_e32 v89, v2
	v_mov_b32_e32 v94, v2
	v_mov_b32_e32 v95, v2
	v_mov_b32_e32 v96, v2
	v_mov_b32_e32 v97, v2
	v_mov_b32_e32 v102, v2
	v_mov_b32_e32 v103, v2
	v_mov_b32_e32 v104, v2
	v_mov_b32_e32 v105, v2
	v_mov_b32_e32 v110, v2
	v_mov_b32_e32 v111, v2
	v_mov_b32_e32 v112, v2
	v_mov_b32_e32 v113, v2
	v_mov_b32_e32 v118, v2
	v_mov_b32_e32 v119, v2
	v_mov_b32_e32 v120, v2
	v_mov_b32_e32 v121, v2
	v_mov_b32_e32 v74, v2
	v_mov_b32_e32 v75, v2
	v_mov_b32_e32 v76, v2
	v_mov_b32_e32 v77, v2
	v_mov_b32_e32 v82, v2
	v_mov_b32_e32 v83, v2
	v_mov_b32_e32 v84, v2
	v_mov_b32_e32 v85, v2
	v_mov_b32_e32 v90, v2
	v_mov_b32_e32 v91, v2
	v_mov_b32_e32 v92, v2
	v_mov_b32_e32 v93, v2
	v_mov_b32_e32 v98, v2
	v_mov_b32_e32 v99, v2
	v_mov_b32_e32 v100, v2
	v_mov_b32_e32 v101, v2
	v_mov_b32_e32 v106, v2
	v_mov_b32_e32 v107, v2
	v_mov_b32_e32 v108, v2
	v_mov_b32_e32 v109, v2
	v_mov_b32_e32 v114, v2
	v_mov_b32_e32 v115, v2
	v_mov_b32_e32 v116, v2
	v_mov_b32_e32 v117, v2
	v_mov_b32_e32 v122, v2
	v_mov_b32_e32 v123, v2
	v_mov_b32_e32 v124, v2
	v_mov_b32_e32 v125, v2
	v_mov_b32_e32 v126, v2
	v_mov_b32_e32 v127, v2
	v_mov_b32_e32 v128, v2
	v_mov_b32_e32 v129, v2

.LBB0_2508:
	s_lshl_b32 s72, s58, 18
	s_and_b64 s[6:7], s[6:7], exec
	v_mov_b32_e32 v2, 0
	s_cselect_b32 s6, s72, s84
	s_add_i32 s7, s84, 0x30800
	s_addk_i32 s79, 0x100
	s_mov_b32 s84, -2
	v_mov_b32_e32 v3, v2
	v_mov_b32_e32 v4, v2
	v_mov_b32_e32 v5, v2
	v_mov_b32_e32 v6, v2
	v_mov_b32_e32 v7, v2
	v_mov_b32_e32 v8, v2
	v_mov_b32_e32 v9, v2
	v_mov_b32_e32 v14, v2
	v_mov_b32_e32 v15, v2
	v_mov_b32_e32 v16, v2
	v_mov_b32_e32 v17, v2
	v_mov_b32_e32 v22, v2
	v_mov_b32_e32 v23, v2
	v_mov_b32_e32 v24, v2
	v_mov_b32_e32 v25, v2
	v_mov_b32_e32 v30, v2
	v_mov_b32_e32 v31, v2
	v_mov_b32_e32 v32, v2
	v_mov_b32_e32 v33, v2
	v_mov_b32_e32 v38, v2
	v_mov_b32_e32 v39, v2
	v_mov_b32_e32 v40, v2
	v_mov_b32_e32 v41, v2
	v_mov_b32_e32 v46, v2
	v_mov_b32_e32 v47, v2
	v_mov_b32_e32 v48, v2
	v_mov_b32_e32 v49, v2
	v_mov_b32_e32 v54, v2
	v_mov_b32_e32 v55, v2
	v_mov_b32_e32 v56, v2
	v_mov_b32_e32 v57, v2
	v_mov_b32_e32 v10, v2
	v_mov_b32_e32 v11, v2
	v_mov_b32_e32 v12, v2
	v_mov_b32_e32 v13, v2
	v_mov_b32_e32 v230, v2
	v_mov_b32_e32 v231, v2
	v_mov_b32_e32 v232, v2
	v_mov_b32_e32 v233, v2
	v_mov_b32_e32 v26, v2
	v_mov_b32_e32 v27, v2
	v_mov_b32_e32 v28, v2
	v_mov_b32_e32 v29, v2
	v_mov_b32_e32 v34, v2
	v_mov_b32_e32 v35, v2
	v_mov_b32_e32 v36, v2
	v_mov_b32_e32 v37, v2
	v_mov_b32_e32 v42, v2
	v_mov_b32_e32 v43, v2
	v_mov_b32_e32 v44, v2
	v_mov_b32_e32 v45, v2
	v_mov_b32_e32 v50, v2
	v_mov_b32_e32 v51, v2
	v_mov_b32_e32 v52, v2
	v_mov_b32_e32 v53, v2
	v_mov_b32_e32 v58, v2
	v_mov_b32_e32 v59, v2
	v_mov_b32_e32 v60, v2
	v_mov_b32_e32 v61, v2
	v_mov_b32_e32 v62, v2
	v_mov_b32_e32 v63, v2
	v_mov_b32_e32 v64, v2
	v_mov_b32_e32 v65, v2
	v_mov_b32_e32 v18, v2
	v_mov_b32_e32 v19, v2
	v_mov_b32_e32 v20, v2
	v_mov_b32_e32 v21, v2
	v_mov_b32_e32 v70, v2
	v_mov_b32_e32 v71, v2
	v_mov_b32_e32 v72, v2
	v_mov_b32_e32 v73, v2
	v_mov_b32_e32 v78, v2
	v_mov_b32_e32 v79, v2
	v_mov_b32_e32 v80, v2
	v_mov_b32_e32 v81, v2
	v_mov_b32_e32 v86, v2
	v_mov_b32_e32 v87, v2
	v_mov_b32_e32 v88, v2
	v_mov_b32_e32 v89, v2
	v_mov_b32_e32 v94, v2
	v_mov_b32_e32 v95, v2
	v_mov_b32_e32 v96, v2
	v_mov_b32_e32 v97, v2
	v_mov_b32_e32 v102, v2
	v_mov_b32_e32 v103, v2
	v_mov_b32_e32 v104, v2
	v_mov_b32_e32 v105, v2
	v_mov_b32_e32 v110, v2
	v_mov_b32_e32 v111, v2
	v_mov_b32_e32 v112, v2
	v_mov_b32_e32 v113, v2
	v_mov_b32_e32 v118, v2
	v_mov_b32_e32 v119, v2
	v_mov_b32_e32 v120, v2
	v_mov_b32_e32 v121, v2
	v_mov_b32_e32 v74, v2
	v_mov_b32_e32 v75, v2
	v_mov_b32_e32 v76, v2
	v_mov_b32_e32 v77, v2
	v_mov_b32_e32 v82, v2
	v_mov_b32_e32 v83, v2
	v_mov_b32_e32 v84, v2
	v_mov_b32_e32 v85, v2
	v_mov_b32_e32 v90, v2
	v_mov_b32_e32 v91, v2
	v_mov_b32_e32 v92, v2
	v_mov_b32_e32 v93, v2
	v_mov_b32_e32 v98, v2
	v_mov_b32_e32 v99, v2
	v_mov_b32_e32 v100, v2
	v_mov_b32_e32 v101, v2
	v_mov_b32_e32 v106, v2
	v_mov_b32_e32 v107, v2
	v_mov_b32_e32 v108, v2
	v_mov_b32_e32 v109, v2
	v_mov_b32_e32 v114, v2
	v_mov_b32_e32 v115, v2
	v_mov_b32_e32 v116, v2
	v_mov_b32_e32 v117, v2
	v_mov_b32_e32 v122, v2
	v_mov_b32_e32 v123, v2
	v_mov_b32_e32 v124, v2
	v_mov_b32_e32 v125, v2
	v_mov_b32_e32 v126, v2
	v_mov_b32_e32 v127, v2
	v_mov_b32_e32 v128, v2
	v_mov_b32_e32 v129, v2

.LBB0_3184:
	s_lshl_b32 s58, s51, 18
	s_and_b64 s[6:7], s[6:7], exec
	v_mov_b32_e32 v2, 0
	s_cselect_b32 s6, s58, s72
	s_add_i32 s7, s72, 0x30800
	s_addk_i32 s71, 0x100
	s_mov_b32 s72, -2
	v_mov_b32_e32 v3, v2
	v_mov_b32_e32 v4, v2
	v_mov_b32_e32 v5, v2
	v_mov_b32_e32 v6, v2
	v_mov_b32_e32 v7, v2
	v_mov_b32_e32 v8, v2
	v_mov_b32_e32 v9, v2
	v_mov_b32_e32 v14, v2
	v_mov_b32_e32 v15, v2
	v_mov_b32_e32 v16, v2
	v_mov_b32_e32 v17, v2
	v_mov_b32_e32 v22, v2
	v_mov_b32_e32 v23, v2
	v_mov_b32_e32 v24, v2
	v_mov_b32_e32 v25, v2
	v_mov_b32_e32 v30, v2
	v_mov_b32_e32 v31, v2
	v_mov_b32_e32 v32, v2
	v_mov_b32_e32 v33, v2
	v_mov_b32_e32 v38, v2
	v_mov_b32_e32 v39, v2
	v_mov_b32_e32 v40, v2
	v_mov_b32_e32 v41, v2
	v_mov_b32_e32 v46, v2
	v_mov_b32_e32 v47, v2
	v_mov_b32_e32 v48, v2
	v_mov_b32_e32 v49, v2
	v_mov_b32_e32 v54, v2
	v_mov_b32_e32 v55, v2
	v_mov_b32_e32 v56, v2
	v_mov_b32_e32 v57, v2
	v_mov_b32_e32 v10, v2
	v_mov_b32_e32 v11, v2
	v_mov_b32_e32 v12, v2
	v_mov_b32_e32 v13, v2
	v_mov_b32_e32 v232, v2
	v_mov_b32_e32 v233, v2
	v_mov_b32_e32 v234, v2
	v_mov_b32_e32 v235, v2
	v_mov_b32_e32 v26, v2
	v_mov_b32_e32 v27, v2
	v_mov_b32_e32 v28, v2
	v_mov_b32_e32 v29, v2
	v_mov_b32_e32 v34, v2
	v_mov_b32_e32 v35, v2
	v_mov_b32_e32 v36, v2
	v_mov_b32_e32 v37, v2
	v_mov_b32_e32 v42, v2
	v_mov_b32_e32 v43, v2
	v_mov_b32_e32 v44, v2
	v_mov_b32_e32 v45, v2
	v_mov_b32_e32 v50, v2
	v_mov_b32_e32 v51, v2
	v_mov_b32_e32 v52, v2
	v_mov_b32_e32 v53, v2
	v_mov_b32_e32 v58, v2
	v_mov_b32_e32 v59, v2
	v_mov_b32_e32 v60, v2
	v_mov_b32_e32 v61, v2
	v_mov_b32_e32 v62, v2
	v_mov_b32_e32 v63, v2
	v_mov_b32_e32 v64, v2
	v_mov_b32_e32 v65, v2
	v_mov_b32_e32 v18, v2
	v_mov_b32_e32 v19, v2
	v_mov_b32_e32 v20, v2
	v_mov_b32_e32 v21, v2
	v_mov_b32_e32 v70, v2
	v_mov_b32_e32 v71, v2
	v_mov_b32_e32 v72, v2
	v_mov_b32_e32 v73, v2
	v_mov_b32_e32 v78, v2
	v_mov_b32_e32 v79, v2
	v_mov_b32_e32 v80, v2
	v_mov_b32_e32 v81, v2
	v_mov_b32_e32 v86, v2
	v_mov_b32_e32 v87, v2
	v_mov_b32_e32 v88, v2
	v_mov_b32_e32 v89, v2
	v_mov_b32_e32 v94, v2
	v_mov_b32_e32 v95, v2
	v_mov_b32_e32 v96, v2
	v_mov_b32_e32 v97, v2
	v_mov_b32_e32 v102, v2
	v_mov_b32_e32 v103, v2
	v_mov_b32_e32 v104, v2
	v_mov_b32_e32 v105, v2
	v_mov_b32_e32 v110, v2
	v_mov_b32_e32 v111, v2
	v_mov_b32_e32 v112, v2
	v_mov_b32_e32 v113, v2
	v_mov_b32_e32 v118, v2
	v_mov_b32_e32 v119, v2
	v_mov_b32_e32 v120, v2
	v_mov_b32_e32 v121, v2
	v_mov_b32_e32 v74, v2
	v_mov_b32_e32 v75, v2
	v_mov_b32_e32 v76, v2
	v_mov_b32_e32 v77, v2
	v_mov_b32_e32 v82, v2
	v_mov_b32_e32 v83, v2
	v_mov_b32_e32 v84, v2
	v_mov_b32_e32 v85, v2
	v_mov_b32_e32 v90, v2
	v_mov_b32_e32 v91, v2
	v_mov_b32_e32 v92, v2
	v_mov_b32_e32 v93, v2
	v_mov_b32_e32 v98, v2
	v_mov_b32_e32 v99, v2
	v_mov_b32_e32 v100, v2
	v_mov_b32_e32 v101, v2
	v_mov_b32_e32 v106, v2
	v_mov_b32_e32 v107, v2
	v_mov_b32_e32 v108, v2
	v_mov_b32_e32 v109, v2
	v_mov_b32_e32 v114, v2
	v_mov_b32_e32 v115, v2
	v_mov_b32_e32 v116, v2
	v_mov_b32_e32 v117, v2
	v_mov_b32_e32 v122, v2
	v_mov_b32_e32 v123, v2
	v_mov_b32_e32 v124, v2
	v_mov_b32_e32 v125, v2
	v_mov_b32_e32 v126, v2
	v_mov_b32_e32 v127, v2
	v_mov_b32_e32 v128, v2
	v_mov_b32_e32 v129, v2
